# retention Q/K stored head-major (A1 rope epilogue store addresses + retention loads): contiguous 32 KB chunks per (b,h)
# speedup vs baseline: 1.0164x; 1.0021x over previous
.LBB0_219:
	v_readlane_b32 s48, v252, 0
	v_readlane_b32 s52, v252, 4
	v_readlane_b32 s53, v252, 5
	s_add_u32 s88, s52, 0x3da00000
	s_addc_u32 s89, s53, 0
	s_add_u32 s0, s52, 0x62a00000
	s_addc_u32 s1, s53, 0
	v_readlane_b32 s49, v252, 1
	v_readlane_b32 s50, v252, 2
	v_readlane_b32 s51, v252, 3
	v_readlane_b32 s54, v252, 6
	v_readlane_b32 s55, v252, 7
	v_writelane_b32 v252, s0, 34
	s_movk_i32 s29, 0x181
	v_mov_b32_e32 v187, 0
	v_writelane_b32 v252, s1, 35
	s_add_u32 s0, s52, 0xd600000
	s_addc_u32 s1, s53, 0
	v_writelane_b32 v252, s0, 36
	v_mbcnt_lo_u32_b32 v0, -1, 0
	s_mov_b32 s92, 0xfffe0000
	v_writelane_b32 v252, s1, 37
	s_add_u32 s0, s52, 0xd800000
	s_addc_u32 s1, s53, 0
	v_writelane_b32 v252, s0, 38
	s_ashr_i32 s24, s2, 31
	s_ashr_i32 s23, s85, 31
	v_writelane_b32 v252, s1, 39
	s_lshr_b32 s0, s24, 29
	s_add_i32 s0, s2, s0
	s_ashr_i32 s8, s0, 3
	s_and_b32 s0, s0, -8
	s_sub_i32 s5, s2, s0
	s_add_u32 s70, s52, 0x4200
	s_addc_u32 s71, s53, 0
	s_add_u32 s0, s52, 0x4400
	s_addc_u32 s1, s53, 0
	s_add_u32 s76, s52, 0x4500
	s_addc_u32 s77, s53, 0
	s_add_u32 s80, s52, 0x4600
	v_writelane_b32 v252, s0, 40
	s_addc_u32 s81, s53, 0
	v_mov_b32_e32 v228, 0x3727c5ac
	v_writelane_b32 v252, s1, 41
	s_add_u32 s0, s52, 0x4700
	s_addc_u32 s1, s53, 0
	v_writelane_b32 v252, s0, 42
	v_mov_b32_e32 v229, 0x260
	v_mbcnt_hi_u32_b32 v230, -1, v0
	v_writelane_b32 v252, s1, 43
	s_add_u32 s0, s52, 0x4800
	s_addc_u32 s1, s53, 0
	v_writelane_b32 v252, s0, 44
	v_mov_b32_e32 v232, 0x43e00000
	v_mov_b32_e32 v248, v187
	v_writelane_b32 v252, s1, 45
	s_add_u32 s0, s52, 0x4900
	s_addc_u32 s1, s53, 0
	v_writelane_b32 v252, s0, 46
	v_mov_b32_e32 v249, v187
	v_mov_b32_e32 v250, v187
	v_writelane_b32 v252, s1, 47
	s_add_u32 s0, s52, 0x4a00
	s_addc_u32 s1, s53, 0
	v_writelane_b32 v252, s0, 48
	v_mov_b32_e32 v251, v187
	v_mov_b32_e32 v234, 0x42800000
	v_writelane_b32 v252, s1, 49
	s_add_u32 s0, s52, 0x4b00
	s_addc_u32 s1, s53, 0
	v_writelane_b32 v252, s0, 50
	v_not_b32_e32 v236, 63
	v_mov_b32_e32 v237, 0xbb000000
	v_writelane_b32 v252, s1, 51
	s_add_u32 s0, s52, 0x4c00
	s_addc_u32 s1, s53, 0
	v_writelane_b32 v252, s0, 52
	v_mov_b32_e32 v233, 0x3b000000
	v_mov_b64_e32 v[240:241], 0x200
	v_writelane_b32 v252, s1, 53
	s_add_u32 s0, s52, 0x4d00
	s_addc_u32 s1, s53, 0
	v_writelane_b32 v252, s0, 54
	v_mov_b64_e32 v[226:227], 0x1ff
	v_mov_b32_e32 v235, 0x3e2aaaab
	v_writelane_b32 v252, s1, 55
	s_add_u32 s0, s52, 0x4e00
	s_addc_u32 s1, s53, 0
	v_writelane_b32 v252, s0, 56
	v_mov_b32_e32 v231, 0x40c00000
	v_mov_b32_e32 v0, 0x3a000000
	v_writelane_b32 v252, s1, 57
	s_add_u32 s0, s52, 0x4f00
	s_addc_u32 s1, s53, 0
	v_writelane_b32 v252, s0, 58
	s_mov_b32 s63, 2
	s_mov_b32 s73, 0xc3160ccd
	v_writelane_b32 v252, s1, 59
	s_add_u32 s0, s52, 0x5000
	s_addc_u32 s1, s53, 0
	v_writelane_b32 v252, s0, 60
	s_mov_b32 s25, 0xc3e00000
	s_mov_b32 s27, 0x41a08000
	v_writelane_b32 v252, s1, 61
	s_add_u32 s0, s52, 0x5100
	s_addc_u32 s1, s53, 0
	v_writelane_b32 v252, s0, 62
	s_mov_b32 s28, 0x45a08000
	s_movk_i32 s31, 0xffd8
	v_writelane_b32 v252, s1, 63
	s_add_u32 s0, s52, 0x5200
	s_addc_u32 s1, s53, 0
	v_writelane_b32 v253, s0, 0
	s_movk_i32 s33, 0xffec
	s_movk_i32 s84, 0xff80
	v_writelane_b32 v253, s1, 1
	s_add_u32 s0, s52, 0x5300
	s_addc_u32 s1, s53, 0
	v_writelane_b32 v253, s0, 2
	s_cmp_eq_u32 s57, 15
	s_mov_b64 s[34:35], 0x80000
	v_writelane_b32 v253, s1, 3
	s_cselect_b64 s[0:1], -1, 0
	v_writelane_b32 v253, s0, 4
	s_cmp_eq_u32 s57, 14
	s_mov_b64 s[86:87], 0x8000
	v_writelane_b32 v253, s1, 5
	s_cselect_b64 s[0:1], -1, 0
	v_writelane_b32 v253, s0, 6
	s_cmp_eq_u32 s57, 13
	s_mov_b32 s93, -1
	v_writelane_b32 v253, s1, 7
	s_cselect_b64 s[0:1], -1, 0
	v_writelane_b32 v253, s0, 8
	s_cmp_eq_u32 s57, 12
	s_mov_b32 s94, 0x3fd744fd
	v_writelane_b32 v253, s1, 9
	s_cselect_b64 s[0:1], -1, 0
	v_writelane_b32 v253, s0, 10
	s_cmp_eq_u32 s57, 11
	s_nop 0
	v_writelane_b32 v253, s1, 11
	s_cselect_b64 s[0:1], -1, 0
	v_writelane_b32 v253, s0, 12
	s_cmp_eq_u32 s57, 10
	s_nop 0
	v_writelane_b32 v253, s1, 13
	s_cselect_b64 s[0:1], -1, 0
	v_writelane_b32 v253, s0, 14
	s_cmp_eq_u32 s57, 9
	s_nop 0
	v_writelane_b32 v253, s1, 15
	s_cselect_b64 s[0:1], -1, 0
	v_writelane_b32 v253, s0, 16
	s_cmp_eq_u32 s57, 8
	s_nop 0
	v_writelane_b32 v253, s1, 17
	s_cselect_b64 s[0:1], -1, 0
	v_writelane_b32 v253, s0, 18
	s_cmp_eq_u32 s57, 7
	s_nop 0
	v_writelane_b32 v253, s1, 19
	s_cselect_b64 s[0:1], -1, 0
	v_writelane_b32 v253, s0, 20
	s_cmp_eq_u32 s57, 6
	s_nop 0
	v_writelane_b32 v253, s1, 21
	s_cselect_b64 s[0:1], -1, 0
	v_writelane_b32 v253, s0, 22
	s_cmp_eq_u32 s57, 5
	s_nop 0
	v_writelane_b32 v253, s1, 23
	s_cselect_b64 s[0:1], -1, 0
	v_writelane_b32 v253, s0, 24
	s_cmp_eq_u32 s57, 4
	s_nop 0
	v_writelane_b32 v253, s1, 25
	s_cselect_b64 s[0:1], -1, 0
	v_writelane_b32 v253, s0, 26
	s_cmp_eq_u32 s57, 3
	s_nop 0
	v_writelane_b32 v253, s1, 27
	s_cselect_b64 s[0:1], -1, 0
	v_writelane_b32 v253, s0, 28
	s_cmp_eq_u32 s57, 2
	s_nop 0
	v_writelane_b32 v253, s1, 29
	s_cselect_b64 s[0:1], -1, 0
	v_writelane_b32 v253, s0, 30
	s_cmp_eq_u32 s57, 1
	s_nop 0
	v_writelane_b32 v253, s1, 31
	s_cselect_b64 s[0:1], -1, 0
	v_writelane_b32 v253, s0, 32
	s_cmp_eq_u32 s57, 0
	s_nop 0
	v_writelane_b32 v253, s1, 33
	s_cselect_b64 s[0:1], -1, 0
	v_writelane_b32 v253, s0, 34
	s_nop 1
	v_writelane_b32 v253, s1, 35
	s_lshl_b32 s0, s57, 8
	s_add_u32 s0, s6, s0
	s_addc_u32 s1, s7, 0
	s_add_u32 s6, s0, 0x1400
	s_addc_u32 s7, s1, 0
	v_writelane_b32 v253, s6, 36
	s_add_u32 s0, s0, 0x2400
	s_addc_u32 s1, s1, 0
	v_writelane_b32 v253, s7, 37
	v_writelane_b32 v253, s0, 38
	s_mov_b32 s57, 0
	s_mov_b32 s96, s57
	v_writelane_b32 v253, s1, 39
	s_add_u32 s0, s52, 0x7400
	s_addc_u32 s1, s53, 0
	v_writelane_b32 v253, s0, 40
	s_nop 1
	v_writelane_b32 v253, s1, 41
	s_add_u32 s0, s52, 0x7500
	s_addc_u32 s1, s53, 0
	v_writelane_b32 v253, s0, 42
	s_cmpk_lt_i32 s2, 0xc00
	s_nop 0
	v_writelane_b32 v253, s1, 43
	s_cselect_b64 s[0:1], -1, 0
	v_writelane_b32 v253, s0, 44
	s_cmpk_lt_i32 s2, 0x100
	s_nop 0
	v_writelane_b32 v253, s1, 45
	s_cselect_b64 s[0:1], -1, 0
	s_lshl_b32 s26, s56, 4
	s_lshl_b32 s10, s85, 4
	v_writelane_b32 v253, s0, 46
	s_cmpk_lt_i32 s2, 0x200
	s_nop 0
	v_writelane_b32 v253, s1, 47
	s_cselect_b64 s[0:1], -1, 0
	s_lshl_b32 s4, s5, 6
	v_writelane_b32 v253, s0, 48
	s_cmpk_lt_i32 s2, 0x400
	s_nop 0
	v_writelane_b32 v253, s1, 49
	s_cselect_b64 s[0:1], -1, 0
	v_writelane_b32 v253, s0, 50
	s_cmp_lt_i32 s5, 0
	s_nop 0
	v_writelane_b32 v253, s1, 51
	s_cselect_b64 s[0:1], -1, 0
	v_writelane_b32 v253, s0, 52
	s_nop 1
	v_writelane_b32 v253, s1, 53
	s_and_b64 s[0:1], s[0:1], exec
	s_cselect_b32 s1, s29, 0x180
	s_mul_i32 s0, s5, 0x41
	s_mul_i32 s1, s5, s1
	s_cselect_b32 s0, s0, s4
	s_add_i32 s1, s1, s8
	s_mul_hi_i32 s4, s1, 0x2aaaaaab
	v_writelane_b32 v253, s5, 54
	s_lshr_b32 s5, s4, 31
	s_ashr_i32 s4, s4, 5
	s_add_i32 s4, s4, s5
	s_mul_i32 s5, s4, 0xc0
	s_sub_i32 s1, s1, s5
	s_bfe_u32 s5, s1, 0x2001d
	s_add_i32 s5, s1, s5
	s_and_b32 s6, s5, 0xfffc
	s_sub_i32 s1, s1, s6
	s_sext_i32_i16 s5, s5
	s_sext_i32_i16 s1, s1
	s_lshl_b32 s6, s4, 2
	s_add_i32 s12, s6, s1
	s_ashr_i32 s1, s5, 2
	s_and_b32 s4, s4, 1
	s_sub_i32 s5, 47, s1
	s_cmp_eq_u32 s4, 0
	s_cselect_b32 s14, s1, s5
	s_add_i32 s0, s0, s8
	s_ashr_i32 s1, s0, 31
	s_lshr_b32 s1, s1, 27
	s_add_i32 s1, s0, s1
	s_and_b32 s4, s1, 0xffe0
	s_sub_i32 s0, s0, s4
	s_bfe_i32 s4, s0, 0x80000
	v_writelane_b32 v253, s8, 55
	s_bfe_u32 s4, s4, 0x2000d
	s_mov_b32 s6, s12
	s_add_i32 s4, s0, s4
	s_ashr_i32 s13, s12, 31
	v_writelane_b32 v253, s6, 56
	s_and_b32 s5, s4, 0xfc
	s_sub_i32 s0, s0, s5
	v_writelane_b32 v253, s7, 57
	s_lshl_b64 s[6:7], s[12:13], 19
	s_ashr_i32 s1, s1, 5
	s_bfe_i32 s4, s4, 0x80000
	v_writelane_b32 v253, s6, 58
	s_sext_i32_i16 s4, s4
	s_sext_i32_i8 s0, s0
	s_lshl_b32 s5, s1, 2
	v_writelane_b32 v253, s7, 59
	s_mov_b32 s6, s14
	s_ashr_i32 s15, s14, 31
	s_add_i32 s8, s5, s0
	s_ashr_i32 s0, s4, 2
	v_writelane_b32 v253, s6, 60
	s_and_b32 s1, s1, 1
	s_sub_i32 s4, 7, s0
	v_writelane_b32 v253, s7, 61
	s_lshl_b64 s[6:7], s[14:15], 19
	v_writelane_b32 v253, s6, 62
	s_cmp_eq_u32 s1, 0
	s_nop 0
	v_writelane_b32 v253, s7, 63
	s_cselect_b32 s6, s0, s4
	s_ashr_i32 s7, s6, 31
	s_lshl_b64 s[4:5], s[6:7], 20
	s_ashr_i32 s9, s8, 31
	v_writelane_b32 v254, s4, 0
	s_lshl_b64 s[0:1], s[8:9], 20
	s_nop 0
	v_writelane_b32 v254, s5, 1
	s_add_u32 s4, s88, s0
	v_writelane_b32 v254, s0, 2
	s_addc_u32 s5, s89, s1
	s_nop 0
	v_writelane_b32 v254, s1, 3
	s_add_u32 s0, s4, 0x80000
	v_writelane_b32 v254, s4, 4
	s_addc_u32 s1, s5, 0
	s_lshl_b32 s50, s85, 9
	v_writelane_b32 v254, s5, 5
	v_writelane_b32 v254, s0, 6
	s_lshl_b32 s4, s2, 9
	s_lshl_b32 s51, s85, 1
	v_writelane_b32 v254, s1, 7
	s_lshl_b32 s0, s56, 10
	v_writelane_b32 v254, s0, 8
	s_lshl_b32 s0, s56, 11
	v_writelane_b32 v254, s0, 9
	s_mov_b32 s0, s10
	s_ashr_i32 s1, s10, 31
	v_writelane_b32 v254, s0, 10
	s_lshl_b32 s30, s85, 10
	s_lshl_b32 s83, s85, 11
	v_writelane_b32 v254, s1, 11
	v_writelane_b32 v254, s4, 12
	s_lshl_b32 s4, s2, 1
	v_writelane_b32 v254, s4, 13
	s_add_i32 s4, 0, 0x22020
	v_writelane_b32 v254, s4, 14
	s_add_i32 s4, 0, 0x22024
	v_writelane_b32 v254, s4, 15
	s_add_i32 s4, 0, 0x18c00
	v_writelane_b32 v254, s4, 16
	s_add_i32 s4, 0, 0x1b000
	v_writelane_b32 v254, s4, 17
	s_add_i32 s4, 0, 0x10800
	v_writelane_b32 v254, s4, 18
	s_add_i32 s4, 0, 0x1d400
	v_writelane_b32 v254, s4, 19
	s_add_i32 s4, 0, 0x18e40
	v_writelane_b32 v254, s4, 20
	s_add_i32 s4, 0, 0x8400
	v_writelane_b32 v254, s4, 21
	s_add_i32 s4, 0, 0x8c40
	v_writelane_b32 v254, s4, 22
	s_add_i32 s4, 0, 0x8420
	v_writelane_b32 v254, s4, 23
	s_add_i32 s4, 0, 0x8c60
	v_writelane_b32 v254, s4, 24
	s_add_i32 s4, 0, 0x1b240
	v_writelane_b32 v254, s4, 25
	s_add_i32 s4, 0, 0x1b020
	v_writelane_b32 v254, s4, 26
	s_add_i32 s4, 0, 0x1b260
	v_writelane_b32 v254, s4, 27
	s_add_i32 s4, 0, 0x1b040
	v_writelane_b32 v254, s4, 28
	s_add_i32 s4, 0, 0x1b280
	v_writelane_b32 v254, s4, 29
	s_add_i32 s4, 0, 0x1b060
	v_writelane_b32 v254, s4, 30
	s_add_i32 s4, 0, 0x1b2a0
	v_writelane_b32 v254, s4, 31
	v_cmp_eq_u32_e64 s[4:5], 0, v238
	s_nop 1
	v_writelane_b32 v254, s4, 32
	s_nop 1
	v_writelane_b32 v254, s5, 33
	s_mov_b32 s4, s8
	v_writelane_b32 v254, s4, 34
	s_nop 1
	v_writelane_b32 v254, s5, 35
	s_lshl_b64 s[4:5], s[8:9], 19
	v_writelane_b32 v254, s4, 36
	s_nop 1
	v_writelane_b32 v254, s5, 37
	s_mov_b32 s4, s6
	v_writelane_b32 v254, s4, 38
	s_nop 1
	v_writelane_b32 v254, s5, 39
	s_lshl_b64 s[4:5], s[6:7], 19
	v_writelane_b32 v254, s4, 40
	s_nop 1
	v_writelane_b32 v254, s5, 41
	s_lshl_b64 s[4:5], s[0:1], 12
	v_writelane_b32 v254, s4, 42
	s_lshl_b64 s[0:1], s[0:1], 13
	s_nop 0
	v_writelane_b32 v254, s5, 43
	v_writelane_b32 v254, s0, 44
	s_nop 1
	v_writelane_b32 v254, s1, 45
	v_writelane_b32 v254, s70, 46
	s_mov_b64 s[0:1], 0x80
	s_nop 0
	v_writelane_b32 v254, s71, 47
	v_writelane_b32 v254, s76, 48
	s_nop 1
	v_writelane_b32 v254, s77, 49
	v_writelane_b32 v254, s80, 50
	s_nop 1
	v_writelane_b32 v254, s81, 51
	v_writelane_b32 v254, s50, 52
	v_writelane_b32 v254, s51, 53
	v_writelane_b32 v254, s3, 54
	v_writelane_b32 v254, s82, 55
	v_writelane_b32 v254, s88, 56
	s_nop 1
	v_writelane_b32 v254, s89, 57
	v_writelane_b32 v254, s26, 58
	v_writelane_b32 v254, s30, 59
	v_writelane_b32 v254, s83, 60
	s_branch .LBB0_223

.LBB0_373:
	s_andn2_b64 vcc, exec, s[46:47]
	v_mov_b32_e32 v238, v186
	v_mov_b64_e32 v[240:241], v[222:223]
	s_cbranch_vccnz .LBB0_375
	s_cmp_lt_i32 s54, 8
	s_cselect_b64 vcc, -1, 0
	v_lshlrev_b32_e32 v1, 9, v30
	s_and_b64 s[46:47], vcc, exec
	s_mov_b32 s21, 0x41a00000
	v_and_b32_e32 v42, 0x1f9e00, v1
	v_mov_b32_e32 v43, v187
	s_cselect_b32 s21, s21, 0x45a00000
	v_lshl_add_u64 v[2:3], v[176:177], 0, v[42:43]
	s_add_u32 s21, s78, s21
	global_load_dwordx4 v[188:191], v[2:3], off
	v_lshl_add_u64 v[4:5], v[174:175], 0, v[42:43]
	s_addc_u32 s39, s79, 0
	s_and_b32 s44, s44, 0x700
	global_load_dwordx4 v[192:195], v[4:5], off
	global_load_dwordx4 v[206:209], v[2:3], off offset:16
	global_load_dwordx4 v[210:213], v[4:5], off offset:16
	s_lshl_b32 s44, s44, 13
	s_add_u32 s44, s21, s44
	v_lshlrev_b32_e32 v186, 1, v170
	s_addc_u32 s45, s39, 0
	v_readfirstlane_b32 s21, v30
	s_nop 0
	s_lshr_b32 s21, s21, 12
	s_mul_i32 s21, s21, 0xe00000
	s_add_u32 s44, s44, s21
	s_addc_u32 s45, s45, 0
	v_lshl_add_u64 v[38:39], s[44:45], 0, v[186:187]
	v_or_b32_e32 v186, 0x2000, v42
	v_lshl_add_u64 v[2:3], v[176:177], 0, v[186:187]
	global_load_dwordx4 v[6:9], v[2:3], off
	s_nop 0
	global_load_dwordx4 v[2:5], v[2:3], off offset:16
	v_lshl_add_u64 v[118:119], v[174:175], 0, v[186:187]
	global_load_dwordx4 v[214:217], v[118:119], off
	global_load_dwordx4 v[218:221], v[118:119], off offset:16
	v_pk_mul_f32 v[118:119], v[152:153], v[184:185]
	v_pk_mul_f32 v[130:131], v[148:149], v[182:183]
	v_mov_b32_e32 v1, 0x3d800000
	v_pk_mul_f32 v[114:115], v[160:161], v[198:199]
	v_pk_mul_f32 v[122:123], v[156:157], v[196:197]
	v_cndmask_b32_e32 v34, 1.0, v1, vcc
	v_lshlrev_b64 v[152:153], 9, v[30:31]
	v_lshl_add_u64 v[156:157], v[38:39], 0, v[152:153]
	v_or_b32_e32 v186, 0x4000, v42
	v_lshl_add_u64 v[160:161], v[176:177], 0, v[186:187]
	v_pk_mul_f32 v[120:121], v[120:121], v[184:185]
	v_pk_mul_f32 v[116:117], v[116:117], v[182:183]
	v_lshlrev_b64 v[20:21], 9, v[20:21]
	v_pk_mul_f32 v[104:105], v[104:105], v[184:185]
	v_pk_mul_f32 v[100:101], v[100:101], v[182:183]
	v_pk_mul_f32 v[108:109], v[108:109], v[196:197]
	v_pk_mul_f32 v[96:97], v[96:97], v[198:199]
	v_pk_mul_f32 v[92:93], v[92:93], v[196:197]
	v_pk_mul_f32 v[88:89], v[88:89], v[184:185]
	v_pk_mul_f32 v[84:85], v[84:85], v[182:183]
	v_pk_mul_f32 v[80:81], v[80:81], v[198:199]
	v_pk_mul_f32 v[72:73], v[72:73], v[184:185]
	v_pk_mul_f32 v[76:77], v[76:77], v[196:197]
	v_pk_mul_f32 v[68:69], v[68:69], v[182:183]
	v_pk_mul_f32 v[56:57], v[56:57], v[184:185]
	v_pk_mul_f32 v[52:53], v[52:53], v[182:183]
	v_pk_mul_f32 v[64:65], v[64:65], v[198:199]
	v_pk_mul_f32 v[60:61], v[60:61], v[196:197]
	s_waitcnt vmcnt(0)
	v_pk_mul_f32 v[134:135], v[118:119], v[190:191]
	v_pk_mul_f32 v[138:139], v[150:151], v[188:189]
	v_pk_mul_f32 v[142:143], v[150:151], v[192:193]
	v_pk_mul_f32 v[148:149], v[130:131], v[208:209]
	v_pk_mul_f32 v[150:151], v[146:147], v[206:207]
	v_pk_mul_f32 v[118:119], v[118:119], v[194:195]
	v_pk_fma_f32 v[134:135], v[114:115], v[194:195], v[134:135] neg_lo:[0,0,1] neg_hi:[0,0,1]
	v_pk_fma_f32 v[138:139], v[158:159], v[192:193], v[138:139] neg_lo:[0,0,1] neg_hi:[0,0,1]
	v_pk_mul_f32 v[130:131], v[130:131], v[212:213]
	v_pk_mul_f32 v[146:147], v[146:147], v[210:211]
	v_pk_fma_f32 v[148:149], v[122:123], v[212:213], v[148:149] neg_lo:[0,0,1] neg_hi:[0,0,1]
	v_pk_fma_f32 v[150:151], v[154:155], v[210:211], v[150:151] neg_lo:[0,0,1] neg_hi:[0,0,1]
	v_pk_fma_f32 v[114:115], v[114:115], v[190:191], v[118:119]
	v_pk_fma_f32 v[118:119], v[158:159], v[188:189], v[142:143]
	v_pk_fma_f32 v[122:123], v[122:123], v[208:209], v[130:131]
	v_pk_fma_f32 v[130:131], v[154:155], v[206:207], v[146:147]
	v_pk_mul_f32 v[134:135], v[34:35], v[134:135] op_sel_hi:[0,1]
	v_pk_mul_f32 v[138:139], v[34:35], v[138:139] op_sel_hi:[0,1]
	v_pk_mul_f32 v[142:143], v[34:35], v[148:149] op_sel_hi:[0,1]
	v_pk_mul_f32 v[148:149], v[34:35], v[150:151] op_sel_hi:[0,1]
	v_pk_mul_f32 v[114:115], v[34:35], v[114:115] op_sel_hi:[0,1]
	v_pk_mul_f32 v[118:119], v[34:35], v[118:119] op_sel_hi:[0,1]
	v_pk_mul_f32 v[122:123], v[34:35], v[122:123] op_sel_hi:[0,1]
	v_pk_mul_f32 v[130:131], v[34:35], v[130:131] op_sel_hi:[0,1]
	v_cvt_pk_bf16_f32 v146, v138, v139
	v_cvt_pk_bf16_f32 v147, v134, v135
	v_cvt_pk_bf16_f32 v148, v148, v149
	v_cvt_pk_bf16_f32 v149, v142, v143
	v_cvt_pk_bf16_f32 v150, v118, v119
	v_cvt_pk_bf16_f32 v151, v114, v115
	v_cvt_pk_bf16_f32 v152, v130, v131
	v_cvt_pk_bf16_f32 v153, v122, v123
	flat_store_dwordx4 v[156:157], v[146:149]
	flat_store_dwordx4 v[156:157], v[150:153] offset:256
	v_lshl_add_u64 v[130:131], v[174:175], 0, v[186:187]
	global_load_dwordx4 v[146:149], v[160:161], off
	global_load_dwordx4 v[150:153], v[160:161], off offset:16
	v_pk_mul_f32 v[118:119], v[140:141], v[196:197]
	v_pk_mul_f32 v[122:123], v[136:137], v[184:185]
	global_load_dwordx4 v[134:137], v[130:131], off offset:16
	global_load_dwordx4 v[138:141], v[130:131], off
	v_pk_mul_f32 v[130:131], v[132:133], v[182:183]
	v_pk_mul_f32 v[114:115], v[144:145], v[198:199]
	v_pk_mul_f32 v[142:143], v[122:123], v[8:9]
	v_pk_mul_f32 v[144:145], v[12:13], v[6:7]
	v_pk_mul_f32 v[154:155], v[130:131], v[4:5]
	v_pk_mul_f32 v[156:157], v[10:11], v[2:3]
	v_pk_mul_f32 v[8:9], v[114:115], v[8:9]
	v_pk_mul_f32 v[6:7], v[16:17], v[6:7]
	v_pk_mul_f32 v[4:5], v[118:119], v[4:5]
	v_pk_mul_f32 v[2:3], v[14:15], v[2:3]
	v_pk_fma_f32 v[114:115], v[114:115], v[216:217], v[142:143] neg_lo:[0,0,1] neg_hi:[0,0,1]
	v_pk_fma_f32 v[16:17], v[16:17], v[214:215], v[144:145] neg_lo:[0,0,1] neg_hi:[0,0,1]
	v_pk_fma_f32 v[118:119], v[118:119], v[220:221], v[154:155] neg_lo:[0,0,1] neg_hi:[0,0,1]
	v_pk_fma_f32 v[14:15], v[14:15], v[218:219], v[156:157] neg_lo:[0,0,1] neg_hi:[0,0,1]
	v_lshlrev_b64 v[132:133], 9, v[202:203]
	v_pk_fma_f32 v[8:9], v[122:123], v[216:217], v[8:9]
	v_pk_fma_f32 v[6:7], v[12:13], v[214:215], v[6:7]
	v_pk_fma_f32 v[4:5], v[130:131], v[220:221], v[4:5]
	v_pk_fma_f32 v[2:3], v[10:11], v[218:219], v[2:3]
	v_pk_mul_f32 v[10:11], v[34:35], v[114:115] op_sel_hi:[0,1]
	v_pk_mul_f32 v[12:13], v[34:35], v[16:17] op_sel_hi:[0,1]
	v_pk_mul_f32 v[16:17], v[34:35], v[118:119] op_sel_hi:[0,1]
	v_pk_mul_f32 v[14:15], v[34:35], v[14:15] op_sel_hi:[0,1]
	v_lshl_add_u64 v[132:133], v[38:39], 0, v[132:133]
	v_or_b32_e32 v186, 0x6000, v42
	v_pk_mul_f32 v[8:9], v[34:35], v[8:9] op_sel_hi:[0,1]
	v_pk_mul_f32 v[6:7], v[34:35], v[6:7] op_sel_hi:[0,1]
	v_pk_mul_f32 v[114:115], v[34:35], v[4:5] op_sel_hi:[0,1]
	v_pk_mul_f32 v[118:119], v[34:35], v[2:3] op_sel_hi:[0,1]
	v_cvt_pk_bf16_f32 v2, v12, v13
	v_cvt_pk_bf16_f32 v3, v10, v11
	v_cvt_pk_bf16_f32 v4, v14, v15
	v_cvt_pk_bf16_f32 v5, v16, v17
	v_lshl_add_u64 v[42:43], v[176:177], 0, v[186:187]
	v_cvt_pk_bf16_f32 v6, v6, v7
	v_cvt_pk_bf16_f32 v7, v8, v9
	v_cvt_pk_bf16_f32 v8, v118, v119
	v_cvt_pk_bf16_f32 v9, v114, v115
	flat_store_dwordx4 v[132:133], v[2:5]
	flat_store_dwordx4 v[132:133], v[6:9] offset:256
	global_load_dwordx4 v[14:17], v[42:43], off
	global_load_dwordx4 v[10:13], v[42:43], off offset:16
	v_lshl_add_u64 v[2:3], v[174:175], 0, v[186:187]
	global_load_dwordx4 v[6:9], v[2:3], off
	s_nop 0
	global_load_dwordx4 v[2:5], v[2:3], off offset:16
	v_pk_mul_f32 v[114:115], v[128:129], v[198:199]
	v_pk_mul_f32 v[118:119], v[124:125], v[196:197]
	v_lshl_add_u64 v[122:123], v[38:39], 0, v[20:21]
	v_add_u32_e32 v42, 0x80, v30
	v_lshlrev_b32_e32 v1, 9, v42
	v_and_b32_e32 v186, 0x1f9e00, v1
	v_lshl_add_u64 v[124:125], v[176:177], 0, v[186:187]
	v_ashrrev_i32_e32 v43, 31, v42
	v_lshlrev_b64 v[42:43], 9, v[42:43]
	v_lshl_add_u64 v[42:43], v[38:39], 0, v[42:43]
	s_waitcnt vmcnt(0)
	v_pk_mul_f32 v[20:21], v[120:121], v[148:149]
	v_pk_mul_f32 v[128:129], v[22:23], v[146:147]
	v_pk_mul_f32 v[130:131], v[116:117], v[152:153]
	v_pk_mul_f32 v[132:133], v[18:19], v[150:151]
	v_pk_mul_f32 v[142:143], v[114:115], v[148:149]
	v_pk_mul_f32 v[144:145], v[126:127], v[146:147]
	v_pk_mul_f32 v[146:147], v[118:119], v[152:153]
	v_pk_mul_f32 v[148:149], v[24:25], v[150:151]
	v_pk_fma_f32 v[20:21], v[114:115], v[140:141], v[20:21] neg_lo:[0,0,1] neg_hi:[0,0,1]
	v_pk_fma_f32 v[114:115], v[126:127], v[138:139], v[128:129] neg_lo:[0,0,1] neg_hi:[0,0,1]
	v_pk_fma_f32 v[118:119], v[118:119], v[136:137], v[130:131] neg_lo:[0,0,1] neg_hi:[0,0,1]
	v_pk_fma_f32 v[24:25], v[24:25], v[134:135], v[132:133] neg_lo:[0,0,1] neg_hi:[0,0,1]
	v_pk_fma_f32 v[120:121], v[120:121], v[140:141], v[142:143]
	v_pk_fma_f32 v[22:23], v[22:23], v[138:139], v[144:145]
	v_pk_fma_f32 v[116:117], v[116:117], v[136:137], v[146:147]
	v_pk_fma_f32 v[18:19], v[18:19], v[134:135], v[148:149]
	v_pk_mul_f32 v[20:21], v[34:35], v[20:21] op_sel_hi:[0,1]
	v_pk_mul_f32 v[114:115], v[34:35], v[114:115] op_sel_hi:[0,1]
	v_pk_mul_f32 v[118:119], v[34:35], v[118:119] op_sel_hi:[0,1]
	v_pk_mul_f32 v[24:25], v[34:35], v[24:25] op_sel_hi:[0,1]
	v_pk_mul_f32 v[120:121], v[34:35], v[120:121] op_sel_hi:[0,1]
	v_pk_mul_f32 v[22:23], v[34:35], v[22:23] op_sel_hi:[0,1]
	v_pk_mul_f32 v[116:117], v[34:35], v[116:117] op_sel_hi:[0,1]
	v_pk_mul_f32 v[126:127], v[34:35], v[18:19] op_sel_hi:[0,1]
	v_cvt_pk_bf16_f32 v18, v114, v115
	v_cvt_pk_bf16_f32 v19, v20, v21
	v_cvt_pk_bf16_f32 v20, v24, v25
	v_cvt_pk_bf16_f32 v21, v118, v119
	v_cvt_pk_bf16_f32 v22, v22, v23
	v_cvt_pk_bf16_f32 v23, v120, v121
	v_cvt_pk_bf16_f32 v24, v126, v127
	v_cvt_pk_bf16_f32 v25, v116, v117
	flat_store_dwordx4 v[122:123], v[18:21]
	flat_store_dwordx4 v[122:123], v[22:25] offset:256
	v_pk_mul_f32 v[120:121], v[112:113], v[198:199]
	global_load_dwordx4 v[18:21], v[124:125], off offset:16
	global_load_dwordx4 v[22:25], v[124:125], off
	v_lshl_add_u64 v[116:117], v[174:175], 0, v[186:187]
	v_lshlrev_b64 v[122:123], 9, v[200:201]
	global_load_dwordx4 v[112:115], v[116:117], off offset:16
	s_nop 0
	global_load_dwordx4 v[116:119], v[116:117], off
	v_mov_b32_e32 v125, v187
	v_lshl_add_u64 v[122:123], v[38:39], 0, v[122:123]
	v_or_b32_e32 v124, 0x2000, v186
	v_lshl_add_u64 v[126:127], v[176:177], 0, v[124:125]
	v_pk_mul_f32 v[128:129], v[104:105], v[16:17]
	v_pk_mul_f32 v[130:131], v[102:103], v[14:15]
	v_pk_mul_f32 v[132:133], v[100:101], v[12:13]
	v_pk_mul_f32 v[134:135], v[98:99], v[10:11]
	v_pk_mul_f32 v[16:17], v[120:121], v[16:17]
	v_pk_mul_f32 v[14:15], v[110:111], v[14:15]
	v_pk_mul_f32 v[12:13], v[108:109], v[12:13]
	v_pk_mul_f32 v[10:11], v[106:107], v[10:11]
	v_pk_fma_f32 v[120:121], v[120:121], v[8:9], v[128:129] neg_lo:[0,0,1] neg_hi:[0,0,1]
	v_pk_fma_f32 v[110:111], v[110:111], v[6:7], v[130:131] neg_lo:[0,0,1] neg_hi:[0,0,1]
	v_pk_fma_f32 v[108:109], v[108:109], v[4:5], v[132:133] neg_lo:[0,0,1] neg_hi:[0,0,1]
	v_pk_fma_f32 v[106:107], v[106:107], v[2:3], v[134:135] neg_lo:[0,0,1] neg_hi:[0,0,1]
	v_pk_fma_f32 v[8:9], v[104:105], v[8:9], v[16:17]
	v_pk_fma_f32 v[6:7], v[102:103], v[6:7], v[14:15]
	v_pk_fma_f32 v[4:5], v[100:101], v[4:5], v[12:13]
	v_pk_fma_f32 v[2:3], v[98:99], v[2:3], v[10:11]
	v_pk_mul_f32 v[10:11], v[34:35], v[120:121] op_sel_hi:[0,1]
	v_pk_mul_f32 v[12:13], v[34:35], v[110:111] op_sel_hi:[0,1]
	v_pk_mul_f32 v[14:15], v[34:35], v[108:109] op_sel_hi:[0,1]
	v_pk_mul_f32 v[16:17], v[34:35], v[106:107] op_sel_hi:[0,1]
	v_pk_mul_f32 v[8:9], v[34:35], v[8:9] op_sel_hi:[0,1]
	v_pk_mul_f32 v[6:7], v[34:35], v[6:7] op_sel_hi:[0,1]
	v_pk_mul_f32 v[98:99], v[34:35], v[4:5] op_sel_hi:[0,1]
	v_pk_mul_f32 v[100:101], v[34:35], v[2:3] op_sel_hi:[0,1]
	v_cvt_pk_bf16_f32 v2, v12, v13
	v_cvt_pk_bf16_f32 v3, v10, v11
	v_cvt_pk_bf16_f32 v4, v16, v17
	v_cvt_pk_bf16_f32 v5, v14, v15
	v_cvt_pk_bf16_f32 v6, v6, v7
	v_cvt_pk_bf16_f32 v7, v8, v9
	v_cvt_pk_bf16_f32 v8, v100, v101
	v_cvt_pk_bf16_f32 v9, v98, v99
	flat_store_dwordx4 v[122:123], v[2:5]
	flat_store_dwordx4 v[122:123], v[6:9] offset:256
	global_load_dwordx4 v[2:5], v[126:127], off
	v_lshl_add_u64 v[14:15], v[174:175], 0, v[124:125]
	global_load_dwordx4 v[6:9], v[14:15], off
	global_load_dwordx4 v[10:13], v[126:127], off offset:16
	s_nop 0
	global_load_dwordx4 v[14:17], v[14:15], off offset:16
	s_waitcnt vmcnt(0)
	v_pk_mul_f32 v[102:103], v[84:85], v[20:21]
	v_pk_mul_f32 v[98:99], v[88:89], v[24:25]
	v_pk_mul_f32 v[100:101], v[86:87], v[22:23]
	v_pk_mul_f32 v[104:105], v[82:83], v[18:19]
	v_pk_mul_f32 v[24:25], v[96:97], v[24:25]
	v_pk_mul_f32 v[22:23], v[94:95], v[22:23]
	v_pk_mul_f32 v[20:21], v[92:93], v[20:21]
	v_pk_mul_f32 v[18:19], v[90:91], v[18:19]
	v_pk_fma_f32 v[96:97], v[96:97], v[118:119], v[98:99] neg_lo:[0,0,1] neg_hi:[0,0,1]
	v_pk_fma_f32 v[94:95], v[94:95], v[116:117], v[100:101] neg_lo:[0,0,1] neg_hi:[0,0,1]
	v_pk_fma_f32 v[92:93], v[92:93], v[114:115], v[102:103] neg_lo:[0,0,1] neg_hi:[0,0,1]
	v_pk_fma_f32 v[90:91], v[90:91], v[112:113], v[104:105] neg_lo:[0,0,1] neg_hi:[0,0,1]
	v_pk_fma_f32 v[24:25], v[88:89], v[118:119], v[24:25]
	v_pk_fma_f32 v[22:23], v[86:87], v[116:117], v[22:23]
	v_pk_fma_f32 v[20:21], v[84:85], v[114:115], v[20:21]
	v_pk_fma_f32 v[18:19], v[82:83], v[112:113], v[18:19]
	v_pk_mul_f32 v[82:83], v[34:35], v[96:97] op_sel_hi:[0,1]
	v_pk_mul_f32 v[84:85], v[34:35], v[94:95] op_sel_hi:[0,1]
	v_pk_mul_f32 v[86:87], v[34:35], v[92:93] op_sel_hi:[0,1]
	v_pk_mul_f32 v[88:89], v[34:35], v[90:91] op_sel_hi:[0,1]
	v_pk_mul_f32 v[24:25], v[34:35], v[24:25] op_sel_hi:[0,1]
	v_pk_mul_f32 v[22:23], v[34:35], v[22:23] op_sel_hi:[0,1]
	v_pk_mul_f32 v[90:91], v[34:35], v[20:21] op_sel_hi:[0,1]
	v_pk_mul_f32 v[92:93], v[34:35], v[18:19] op_sel_hi:[0,1]
	v_cvt_pk_bf16_f32 v18, v84, v85
	v_cvt_pk_bf16_f32 v19, v82, v83
	v_cvt_pk_bf16_f32 v20, v88, v89
	v_cvt_pk_bf16_f32 v21, v86, v87
	v_cvt_pk_bf16_f32 v22, v22, v23
	v_cvt_pk_bf16_f32 v23, v24, v25
	v_cvt_pk_bf16_f32 v24, v92, v93
	v_cvt_pk_bf16_f32 v25, v90, v91
	v_or_b32_e32 v82, 0x4000, v186
	v_mov_b32_e32 v83, v187
	flat_store_dwordx4 v[42:43], v[18:21]
	flat_store_dwordx4 v[42:43], v[22:25] offset:256
	v_lshl_add_u64 v[86:87], v[176:177], 0, v[82:83]
	v_add_u32_e32 v42, 0x90, v30
	v_lshl_add_u64 v[22:23], v[174:175], 0, v[82:83]
	global_load_dwordx4 v[18:21], v[22:23], off offset:16
	s_nop 0
	global_load_dwordx4 v[22:25], v[22:23], off
	s_nop 0
	global_load_dwordx4 v[82:85], v[86:87], off offset:16
	s_nop 0
	global_load_dwordx4 v[86:89], v[86:87], off
	v_ashrrev_i32_e32 v43, 31, v42
	v_or_b32_e32 v186, 0x6000, v186
	v_pk_mul_f32 v[92:93], v[70:71], v[2:3]
	v_pk_mul_f32 v[2:3], v[78:79], v[2:3]
	v_pk_mul_f32 v[90:91], v[72:73], v[4:5]
	v_pk_mul_f32 v[4:5], v[80:81], v[4:5]
	v_pk_fma_f32 v[2:3], v[70:71], v[6:7], v[2:3]
	v_pk_fma_f32 v[90:91], v[80:81], v[8:9], v[90:91] neg_lo:[0,0,1] neg_hi:[0,0,1]
	v_pk_mul_f32 v[94:95], v[68:69], v[12:13]
	v_pk_mul_f32 v[96:97], v[66:67], v[10:11]
	v_pk_fma_f32 v[4:5], v[72:73], v[8:9], v[4:5]
	v_pk_mul_f32 v[8:9], v[34:35], v[2:3] op_sel_hi:[0,1]
	v_pk_mul_f32 v[2:3], v[76:77], v[12:13]
	v_pk_fma_f32 v[92:93], v[78:79], v[6:7], v[92:93] neg_lo:[0,0,1] neg_hi:[0,0,1]
	v_pk_fma_f32 v[94:95], v[76:77], v[16:17], v[94:95] neg_lo:[0,0,1] neg_hi:[0,0,1]
	v_pk_fma_f32 v[96:97], v[74:75], v[14:15], v[96:97] neg_lo:[0,0,1] neg_hi:[0,0,1]
	v_pk_mul_f32 v[6:7], v[34:35], v[4:5] op_sel_hi:[0,1]
	v_pk_mul_f32 v[4:5], v[74:75], v[10:11]
	v_pk_fma_f32 v[2:3], v[68:69], v[16:17], v[2:3]
	v_pk_mul_f32 v[90:91], v[34:35], v[90:91] op_sel_hi:[0,1]
	v_pk_mul_f32 v[92:93], v[34:35], v[92:93] op_sel_hi:[0,1]
	v_pk_mul_f32 v[94:95], v[34:35], v[94:95] op_sel_hi:[0,1]
	v_pk_mul_f32 v[96:97], v[34:35], v[96:97] op_sel_hi:[0,1]
	v_pk_fma_f32 v[4:5], v[66:67], v[14:15], v[4:5]
	v_pk_mul_f32 v[10:11], v[34:35], v[2:3] op_sel_hi:[0,1]
	v_lshlrev_b64 v[2:3], 9, v[42:43]
	v_pk_mul_f32 v[12:13], v[34:35], v[4:5] op_sel_hi:[0,1]
	v_lshl_add_u64 v[14:15], v[38:39], 0, v[2:3]
	v_cvt_pk_bf16_f32 v2, v92, v93
	v_cvt_pk_bf16_f32 v3, v90, v91
	v_cvt_pk_bf16_f32 v4, v96, v97
	v_cvt_pk_bf16_f32 v5, v94, v95
	flat_store_dwordx4 v[14:15], v[2:5]
	v_add_u32_e32 v42, 0xa0, v30
	v_ashrrev_i32_e32 v43, 31, v42
	v_cvt_pk_bf16_f32 v2, v8, v9
	v_cvt_pk_bf16_f32 v3, v6, v7
	v_cvt_pk_bf16_f32 v4, v12, v13
	v_cvt_pk_bf16_f32 v5, v10, v11
	flat_store_dwordx4 v[14:15], v[2:5] offset:256
	v_lshl_add_u64 v[10:11], v[176:177], 0, v[186:187]
	global_load_dwordx4 v[2:5], v[10:11], off
	v_lshl_add_u64 v[14:15], v[174:175], 0, v[186:187]
	global_load_dwordx4 v[6:9], v[14:15], off
	s_nop 0
	global_load_dwordx4 v[10:13], v[10:11], off offset:16
	s_nop 0
	global_load_dwordx4 v[14:17], v[14:15], off offset:16
	s_waitcnt vmcnt(0)
	v_pk_mul_f32 v[72:73], v[50:51], v[82:83]
	v_pk_mul_f32 v[68:69], v[54:55], v[86:87]
	v_pk_mul_f32 v[66:67], v[56:57], v[88:89]
	v_pk_mul_f32 v[70:71], v[52:53], v[84:85]
	v_pk_mul_f32 v[76:77], v[62:63], v[86:87]
	v_pk_fma_f32 v[62:63], v[62:63], v[22:23], v[68:69] neg_lo:[0,0,1] neg_hi:[0,0,1]
	v_pk_fma_f32 v[68:69], v[58:59], v[18:19], v[72:73] neg_lo:[0,0,1] neg_hi:[0,0,1]
	v_pk_mul_f32 v[58:59], v[58:59], v[82:83]
	v_pk_mul_f32 v[74:75], v[64:65], v[88:89]
	v_pk_fma_f32 v[64:65], v[64:65], v[24:25], v[66:67] neg_lo:[0,0,1] neg_hi:[0,0,1]
	v_pk_fma_f32 v[66:67], v[60:61], v[20:21], v[70:71] neg_lo:[0,0,1] neg_hi:[0,0,1]
	v_pk_mul_f32 v[60:61], v[60:61], v[84:85]
	v_pk_fma_f32 v[18:19], v[50:51], v[18:19], v[58:59]
	v_pk_fma_f32 v[24:25], v[56:57], v[24:25], v[74:75]
	v_pk_fma_f32 v[22:23], v[54:55], v[22:23], v[76:77]
	v_pk_mul_f32 v[54:55], v[34:35], v[64:65] op_sel_hi:[0,1]
	v_pk_mul_f32 v[56:57], v[34:35], v[62:63] op_sel_hi:[0,1]
	v_pk_mul_f32 v[62:63], v[34:35], v[66:67] op_sel_hi:[0,1]
	v_pk_mul_f32 v[64:65], v[34:35], v[68:69] op_sel_hi:[0,1]
	v_pk_fma_f32 v[20:21], v[52:53], v[20:21], v[60:61]
	v_pk_mul_f32 v[52:53], v[34:35], v[18:19] op_sel_hi:[0,1]
	v_lshlrev_b64 v[18:19], 9, v[42:43]
	v_pk_mul_f32 v[24:25], v[34:35], v[24:25] op_sel_hi:[0,1]
	v_pk_mul_f32 v[22:23], v[34:35], v[22:23] op_sel_hi:[0,1]
	v_pk_mul_f32 v[50:51], v[34:35], v[20:21] op_sel_hi:[0,1]
	v_lshl_add_u64 v[42:43], v[38:39], 0, v[18:19]
	v_cvt_pk_bf16_f32 v18, v56, v57
	v_cvt_pk_bf16_f32 v19, v54, v55
	v_cvt_pk_bf16_f32 v20, v64, v65
	v_cvt_pk_bf16_f32 v21, v62, v63
	flat_store_dwordx4 v[42:43], v[18:21]
	s_nop 1
	v_cvt_pk_bf16_f32 v18, v22, v23
	v_cvt_pk_bf16_f32 v19, v24, v25
	v_cvt_pk_bf16_f32 v20, v52, v53
	v_cvt_pk_bf16_f32 v21, v50, v51
	flat_store_dwordx4 v[42:43], v[18:21] offset:256
	v_pk_mul_f32 v[24:25], v[40:41], v[184:185]
	v_pk_mul_f32 v[22:23], v[44:45], v[196:197]
	v_pk_mul_f32 v[20:21], v[48:49], v[198:199]
	v_add_u32_e32 v18, 0xb0, v30
	v_pk_mul_f32 v[30:31], v[36:37], v[182:183]
	v_pk_mul_f32 v[36:37], v[24:25], v[4:5]
	v_pk_mul_f32 v[4:5], v[20:21], v[4:5]
	v_pk_mul_f32 v[40:41], v[28:29], v[2:3]
	v_pk_mul_f32 v[2:3], v[46:47], v[2:3]
	v_pk_fma_f32 v[4:5], v[24:25], v[8:9], v[4:5]
	v_pk_fma_f32 v[40:41], v[46:47], v[6:7], v[40:41] neg_lo:[0,0,1] neg_hi:[0,0,1]
	v_pk_mul_f32 v[42:43], v[30:31], v[12:13]
	v_pk_mul_f32 v[44:45], v[26:27], v[10:11]
	v_pk_fma_f32 v[6:7], v[28:29], v[6:7], v[2:3]
	v_pk_mul_f32 v[2:3], v[34:35], v[4:5] op_sel_hi:[0,1]
	v_pk_mul_f32 v[4:5], v[22:23], v[12:13]
	v_pk_fma_f32 v[36:37], v[20:21], v[8:9], v[36:37] neg_lo:[0,0,1] neg_hi:[0,0,1]
	v_pk_fma_f32 v[42:43], v[22:23], v[16:17], v[42:43] neg_lo:[0,0,1] neg_hi:[0,0,1]
	v_pk_fma_f32 v[44:45], v[32:33], v[14:15], v[44:45] neg_lo:[0,0,1] neg_hi:[0,0,1]
	v_pk_mul_f32 v[28:29], v[34:35], v[6:7] op_sel_hi:[0,1]
	v_pk_mul_f32 v[6:7], v[32:33], v[10:11]
	v_pk_fma_f32 v[4:5], v[30:31], v[16:17], v[4:5]
	v_ashrrev_i32_e32 v19, 31, v18
	v_pk_mul_f32 v[36:37], v[34:35], v[36:37] op_sel_hi:[0,1]
	v_pk_mul_f32 v[40:41], v[34:35], v[40:41] op_sel_hi:[0,1]
	v_pk_mul_f32 v[42:43], v[34:35], v[42:43] op_sel_hi:[0,1]
	v_pk_mul_f32 v[44:45], v[34:35], v[44:45] op_sel_hi:[0,1]
	v_pk_fma_f32 v[8:9], v[26:27], v[14:15], v[6:7]
	v_pk_mul_f32 v[6:7], v[34:35], v[4:5] op_sel_hi:[0,1]
	v_lshlrev_b64 v[4:5], 9, v[18:19]
	v_pk_mul_f32 v[26:27], v[34:35], v[8:9] op_sel_hi:[0,1]
	v_lshl_add_u64 v[4:5], v[38:39], 0, v[4:5]
	v_cvt_pk_bf16_f32 v8, v40, v41
	v_cvt_pk_bf16_f32 v9, v36, v37
	v_cvt_pk_bf16_f32 v10, v44, v45
	v_cvt_pk_bf16_f32 v11, v42, v43
	flat_store_dwordx4 v[4:5], v[8:11]

.LBB0_431:
	s_andn2_b64 vcc, exec, s[16:17]
	s_cbranch_vccnz .LBB0_490
	v_readlane_b32 s4, v253, 46
	v_mov_b32_e32 v2, v238
	v_readlane_b32 s5, v253, 47
	s_andn2_b64 vcc, exec, s[4:5]
	v_readfirstlane_b32 s11, v2
	s_cbranch_vccnz .LBB0_440
	s_add_u32 s16, s78, 0x41a00000
	s_addc_u32 s17, s79, 0
	s_add_u32 s18, s78, 0x45a00000
	s_addc_u32 s19, s79, 0
	s_add_u32 s20, s78, 0x49a00000
	s_addc_u32 s21, s79, 0
	s_add_u32 s7, s78, 0x59a00000
	s_addc_u32 s10, s79, 0
	s_movk_i32 s12, 0x840
	v_ashrrev_i32_e32 v78, 3, v2
	s_waitcnt lgkmcnt(0)
	v_and_b32_e32 v6, 7, v2
	s_ashr_i32 s13, s11, 3
	v_cmp_gt_i32_e32 vcc, s12, v2
	v_lshlrev_b32_e32 v4, 3, v6
	v_lshlrev_b32_e32 v12, 4, v6
	v_sub_u32_e32 v6, 63, v78
	s_lshr_b32 s12, s11, 5
	v_bfi_b32 v13, -16, s13, v2
	s_movk_i32 s8, 0x210
	v_bfe_u32 v3, v2, 4, 2
	v_cvt_f32_i32_e32 v91, v6
	s_and_b32 s12, s12, 2
	v_mul_lo_u32 v6, v13, s8
	v_and_b32_e32 v1, 15, v2
	s_and_b32 s14, s13, -16
	v_add_u32_e32 v14, 0, v6
	s_lshl_b32 s15, s12, 4
	v_lshlrev_b32_e32 v6, 2, v3
	v_or_b32_e32 v16, s15, v1
	v_or_b32_e32 v18, s14, v6
	v_sub_u32_e32 v27, v18, v16
	v_sub_u32_e32 v28, 0, v27
	v_or_b32_e32 v19, 16, v16
	v_max_i32_e32 v27, v27, v28
	v_cvt_f32_u32_e32 v129, v27
	v_sub_u32_e32 v27, v18, v19
	v_sub_u32_e32 v28, 0, v27
	s_movk_i32 s4, 0x90
	v_max_i32_e32 v27, v27, v28
	v_readlane_b32 s36, v254, 19
	v_cvt_f32_u32_e32 v130, v27
	v_mul_lo_u32 v27, v18, s4
	v_add_u32_e32 v131, s36, v27
	v_or_b32_e32 v27, 1, v18
	v_sub_u32_e32 v28, v27, v16
	v_sub_u32_e32 v29, 0, v28
	v_max_i32_e32 v28, v28, v29
	v_sub_u32_e32 v27, v27, v19
	v_cvt_f32_u32_e32 v132, v28
	v_sub_u32_e32 v28, 0, v27
	v_max_i32_e32 v27, v27, v28
	v_cvt_f32_u32_e32 v133, v27
	v_or_b32_e32 v27, 2, v18
	v_sub_u32_e32 v28, v27, v16
	v_sub_u32_e32 v29, 0, v28
	v_readlane_b32 s9, v254, 18
	v_max_i32_e32 v28, v28, v29
	v_sub_u32_e32 v27, v27, v19
	v_mov_b32_e32 v20, s9
	v_cvt_f32_u32_e32 v135, v28
	v_sub_u32_e32 v28, 0, v27
	v_or_b32_e32 v18, 3, v18
	v_mad_u32_u24 v17, v16, s8, 0
	v_lshlrev_b32_e32 v126, 1, v16
	v_mad_u32_u24 v20, v16, s8, v20
	v_max_i32_e32 v27, v27, v28
	v_sub_u32_e32 v16, v18, v16
	v_cvt_f32_u32_e32 v136, v27
	v_sub_u32_e32 v27, 0, v16
	v_max_i32_e32 v16, v16, v27
	v_cvt_f32_u32_e32 v138, v16
	v_sub_u32_e32 v16, v18, v19
	v_add_u32_e32 v21, 1, v13
	v_sub_u32_e32 v18, 0, v16
	v_lshlrev_b32_e32 v5, 3, v2
	v_lshlrev_b32_e32 v15, 4, v3
	v_cvt_f32_i32_e32 v128, v21
	v_bfe_u32 v21, v2, 2, 2
	v_lshlrev_b32_e32 v3, 3, v3
	v_max_i32_e32 v16, v16, v18
	v_and_b32_e32 v7, 0xf8, v5
	v_and_b32_e32 v5, 24, v5
	s_ashr_i32 s22, s14, 31
	v_or_b32_e32 v80, s14, v1
	s_and_b32 s14, s11, 0xffffffc0
	v_cvt_f32_u32_e32 v139, v16
	v_or_b32_e32 v16, v3, v21
	v_mul_lo_u32 v10, v78, s4
	v_mul_lo_u32 v13, v13, s4
	s_lshl_b32 s12, s12, 5
	v_or_b32_e32 v22, s14, v5
	v_mad_u32_u24 v5, v16, s4, v5
	v_readlane_b32 s4, v254, 20
	v_readlane_b32 s5, v254, 16
	v_lshlrev_b32_e32 v127, 1, v19
	s_or_b32 s13, s12, 32
	v_add_u32_e32 v19, s4, v5
	v_add_u32_e32 v18, s5, v5
	v_add_u32_e32 v142, s12, v19
	v_add_u32_e32 v144, s13, v19
	v_add_u32_e32 v19, 0x1200, v5
	v_readlane_b32 s6, v254, 17
	v_add_u32_e32 v13, s36, v13
	v_mov_b32_e32 v81, s22
	v_add_u32_e32 v141, s12, v18
	v_add_u32_e32 v143, s13, v18
	v_or_b32_e32 v18, 32, v16
	v_add_u32_e32 v21, s5, v19
	v_add_u32_e32 v27, s4, v19
	v_readlane_b32 s22, v254, 25
	v_readlane_b32 s36, v254, 26
	v_readlane_b32 s37, v254, 27
	v_readlane_b32 s38, v254, 28
	v_readlane_b32 s39, v254, 29
	v_readlane_b32 s40, v254, 30
	v_readlane_b32 s41, v254, 31
	v_add_u32_e32 v145, s12, v21
	v_add_u32_e32 v146, s12, v27
	v_mad_u32_u24 v16, v16, s8, v22
	v_add_u32_e32 v150, s6, v5
	v_readlane_b32 s12, v254, 23
	v_add_u32_e32 v154, s22, v5
	v_add_u32_e32 v155, s36, v5
	v_add_u32_e32 v156, s37, v5
	v_add_u32_e32 v157, s38, v5
	v_add_u32_e32 v158, s39, v5
	v_add_u32_e32 v159, s40, v5
	v_add_u32_e32 v160, s41, v5
	v_mad_u32_u24 v5, v18, s8, v22
	v_add_u32_e32 v11, s5, v10
	v_add_u32_e32 v23, 0x200, v2
	v_add_u32_e32 v147, s13, v21
	v_add_u32_e32 v148, s13, v27
	v_readlane_b32 s4, v254, 21
	v_readlane_b32 s5, v254, 22
	v_add_u32_e32 v152, s12, v16
	v_readlane_b32 s13, v254, 24
	v_add_u32_e32 v164, s12, v5
	s_add_i32 s12, s9, s14
	v_ashrrev_i32_e32 v84, 5, v23
	v_add_u32_e32 v23, 0x400, v2
	v_add_u32_e32 v161, s4, v5
	v_add_u32_e32 v163, s5, v5
	v_add_u32_e32 v165, s13, v5
	v_add_u32_e32 v5, s12, v3
	s_add_i32 s12, s14, 0
	v_ashrrev_i32_e32 v79, 31, v78
	v_lshlrev_b32_e32 v8, 4, v2
	v_ashrrev_i32_e32 v86, 5, v23
	v_add_u32_e32 v23, 0x600, v2
	s_add_i32 s12, s12, 0x10820
	v_and_b32_e32 v9, 0x1f0, v8
	v_ashrrev_i32_e32 v82, 5, v2
	v_ashrrev_i32_e32 v88, 5, v23
	v_add_u32_e32 v149, s4, v16
	v_add_u32_e32 v151, s5, v16
	v_add_u32_e32 v153, s13, v16
	v_add_u32_e32 v16, s12, v3
	v_add_u32_e32 v173, 0xfffffe00, v2
	v_and_or_b32 v90, s11, 64, v3
	v_lshlrev_b64 v[2:3], 13, v[78:79]
	v_add_u32_e32 v9, 0, v9
	v_add_u32_e32 v10, s6, v10
	v_ashrrev_i32_e32 v83, 31, v82
	v_ashrrev_i32_e32 v85, 31, v84
	v_ashrrev_i32_e32 v87, 31, v86
	v_ashrrev_i32_e32 v89, 31, v88
	v_mul_lo_u32 v23, v82, s8
	v_mul_lo_u32 v24, v84, s8
	v_mul_lo_u32 v25, v86, s8
	v_mul_lo_u32 v26, v88, s8
	v_mul_u32_u24_e32 v1, 0x210, v1
	v_or_b32_e32 v2, v2, v12
	s_mov_b64 s[12:13], 0x49a80000
	v_add_u32_e32 v134, 0x90, v131
	v_add_u32_e32 v137, 0x120, v131
	v_add_u32_e32 v140, 0x1b0, v131
	v_add_u32_e32 v162, s6, v19
	v_add_u32_e32 v166, s22, v19
	v_add_u32_e32 v167, s36, v19
	v_add_u32_e32 v168, s37, v19
	v_add_u32_e32 v169, s38, v19
	v_add_u32_e32 v170, s39, v19
	v_add_u32_e32 v171, s40, v19
	v_add_u32_e32 v172, s41, v19
	v_add_u32_e32 v174, s9, v8
	v_lshl_add_u64 v[92:93], v[2:3], 0, s[12:13]
	v_lshlrev_b64 v[94:95], 9, v[88:89]
	v_lshlrev_b64 v[96:97], 9, v[86:87]
	v_lshlrev_b64 v[98:99], 9, v[84:85]
	v_lshlrev_b64 v[100:101], 9, v[82:83]
	v_lshlrev_b32_e32 v175, 1, v7
	v_lshlrev_b32_e32 v102, 1, v4
	v_lshlrev_b32_e32 v186, 1, v6
	s_lshl_b32 s56, s15, 1
	v_add_u32_e32 v176, v9, v23
	v_add_u32_e32 v177, v9, v24
	v_add_u32_e32 v178, v9, v25
	v_add_u32_e32 v179, v9, v26
	v_add_u32_e32 v180, v11, v12
	v_add_u32_e32 v181, v10, v12
	v_add_u32_e32 v182, v14, v15
	v_add_u32_e32 v183, v17, v15
	v_add_u32_e32 v184, v20, v15
	v_add_u32_e32 v185, v13, v15
	v_add_u32_e32 v196, v5, v1
	v_add_u32_e32 v197, v16, v1
	v_readlane_b32 s11, v254, 13
	s_mov_b32 s12, s2
	v_readlane_b32 s13, v254, 12
	s_mov_b32 s14, s2

.LBB0_437:
	s_or_b64 exec, exec, s[38:39]
	s_and_b32 s36, s13, 0x3000
	s_mov_b32 s37, s57
	v_lshl_add_u64 v[2:3], v[80:81], 0, s[36:37]
	s_and_b32 s36, s11, 0xffffffc0
	s_and_b32 s15, s12, 7
	s_ashr_i32 s37, s36, 31
	s_lshl_b32 s38, s15, 10
	s_lshl_b64 s[36:37], s[36:37], 1
	s_add_u32 s36, s36, s38
	v_lshlrev_b64 v[2:3], 13, v[2:3]
	s_addc_u32 s37, s37, 0
	s_lshl_b32 s38, s13, 13
	v_or_b32_e32 v2, v90, v2
	s_and_b32 s38, s38, 0x6000000
	v_lshl_add_u64 v[112:113], s[36:37], 0, v[2:3]
	s_add_u32 s36, s36, s38
	s_addc_u32 s37, s37, 0
	v_lshl_add_u64 v[114:115], s[36:37], 0, v[92:93]
	s_lshl_b32 s36, s13, 12
	s_and_b32 s36, s36, 0x3000000
	s_mov_b32 s37, s57
	v_lshl_add_u64 v[2:3], v[94:95], 0, s[36:37]
	v_lshl_or_b32 v4, s15, 21, v175
	v_mov_b32_e32 v5, v187
	s_and_b32 s40, s14, 7
	v_lshl_add_u64 v[116:117], v[2:3], 0, v[4:5]
	v_lshl_add_u64 v[2:3], v[96:97], 0, s[36:37]
	v_cvt_f32_ubyte0_e32 v1, s40
	v_lshl_add_u64 v[118:119], v[2:3], 0, v[4:5]
	v_lshl_add_u64 v[2:3], v[98:99], 0, s[36:37]
	v_sub_f32_e32 v1, 0xc0a00000, v1
	v_lshl_add_u64 v[120:121], v[2:3], 0, v[4:5]
	v_lshl_add_u64 v[2:3], v[100:101], 0, s[36:37]
	v_cmp_gt_f32_e64 s[36:37], s52, v1
	v_lshl_add_u64 v[122:123], v[2:3], 0, v[4:5]
	v_mov_b32_e32 v103, v187
	v_cndmask_b32_e64 v2, 0, v234, s[36:37]
	v_add_f32_e32 v1, v1, v2
	v_exp_f32_e32 v1, v1
	s_and_b64 s[36:37], s[36:37], exec
	s_cselect_b32 s15, 0xffffffc0, 0
	v_mov_b32_e32 v2, 0x42000000
	v_ldexp_f32 v1, v1, s15
	v_sub_f32_e32 v1, 1.0, v1
	s_mov_b32 s15, 0x800000
	v_cmp_gt_f32_e64 s[36:37], s15, v1
	s_and_b64 s[38:39], s[36:37], exec
	s_cselect_b32 s15, 32, 0
	v_ldexp_f32 v1, v1, s15
	v_log_f32_e32 v1, v1
	v_cndmask_b32_e64 v2, 0, v2, s[36:37]
	s_mov_b32 s39, s57
	v_sub_f32_e32 v1, v1, v2
	v_mul_f32_e32 v2, 0x42800000, v1
	v_cmp_gt_f32_e64 s[36:37], s52, v2
	v_mul_f32_e32 v38, v1, v91
	s_nop 0
	v_cndmask_b32_e64 v2, 0, v234, s[36:37]
	v_fmac_f32_e32 v2, 0x42800000, v1
	v_exp_f32_e32 v2, v2
	s_and_b64 s[36:37], s[36:37], exec
	s_cselect_b32 s15, 0xffffffc0, 0
	s_lshl_b32 s36, s40, 10
	v_ldexp_f32 v104, v2, s15
	s_lshl_b32 s15, s14, 9
	s_and_b32 s38, s15, 0x3000
	s_lshl_b32 s15, s40, 9
	s_lshl_b32 s100, s40, 21
	v_or_b32_e32 v28, s100, v175
	s_lshl_b32 s100, s38, 3
	s_mov_b32 s101, 0
	v_lshl_add_u64 v[26:27], s[100:101], 0, v[88:89]
	v_lshl_add_u64 v[2:3], s[100:101], 0, v[82:83]
	v_lshl_add_u64 v[10:11], s[100:101], 0, v[84:85]
	v_lshl_add_u64 v[18:19], s[100:101], 0, v[86:87]
	v_lshlrev_b64 v[26:27], 9, v[26:27]
	v_lshlrev_b64 v[6:7], 9, v[2:3]
	v_lshlrev_b64 v[14:15], 9, v[10:11]
	v_lshlrev_b64 v[22:23], 9, v[18:19]
	v_or_b32_e32 v26, v26, v28
	v_or_b32_e32 v6, v6, v28
	v_or_b32_e32 v14, v14, v28
	v_or_b32_e32 v22, v22, v28
	v_lshl_add_u64 v[28:29], s[16:17], 0, v[26:27]
	v_lshl_add_u64 v[26:27], s[18:19], 0, v[26:27]
	global_load_dwordx4 v[30:33], v[28:29], off
	global_load_dwordx4 v[34:37], v[26:27], off
	v_lshl_add_u64 v[26:27], s[38:39], 0, v[78:79]
	v_lshlrev_b64 v[26:27], 13, v[26:27]
	v_lshl_add_u64 v[26:27], s[20:21], 0, v[26:27]
	s_mov_b32 s37, s57
	v_lshl_add_u64 v[26:27], v[26:27], 0, s[36:37]
	s_lshl_b32 s36, s14, 1
	s_and_b32 s40, s36, 0xffffffc0
	s_ashr_i32 s41, s40, 31
	v_lshl_add_u64 v[26:27], s[40:41], 1, v[26:27]
	v_lshl_add_u64 v[2:3], s[16:17], 0, v[6:7]
	v_lshl_add_u64 v[6:7], s[18:19], 0, v[6:7]
	v_lshl_add_u64 v[10:11], s[16:17], 0, v[14:15]
	v_lshl_add_u64 v[14:15], s[18:19], 0, v[14:15]
	v_lshl_add_u64 v[18:19], s[16:17], 0, v[22:23]
	v_lshl_add_u64 v[22:23], s[18:19], 0, v[22:23]
	v_lshl_add_u64 v[26:27], v[26:27], 0, v[102:103]
	v_cmp_gt_f32_e64 s[36:37], s52, v38
	global_load_dwordx4 v[2:5], v[2:3], off
	v_mov_b32_e32 v106, v104
	global_load_dwordx4 v[6:9], v[6:7], off
	v_cndmask_b32_e64 v38, 0, v234, s[36:37]
	global_load_dwordx4 v[10:13], v[10:11], off
	v_fmac_f32_e32 v38, v1, v91
	global_load_dwordx4 v[14:17], v[14:15], off
	v_exp_f32_e32 v38, v38
	global_load_dwordx4 v[18:21], v[18:19], off
	v_cndmask_b32_e64 v39, 0, v236, s[36:37]
	global_load_dwordx4 v[22:25], v[22:23], off
	v_ldexp_f32 v124, v38, v39
	global_load_dwordx4 v[26:29], v[26:27], off
	v_mul_f32_e32 v38, v1, v128
	v_cmp_gt_f32_e64 s[36:37], s52, v38
	v_mov_b32_e32 v107, v104
	v_mov_b32_e32 v125, v124
	v_cndmask_b32_e64 v38, 0, v234, s[36:37]
	v_fmac_f32_e32 v38, v1, v128
	v_exp_f32_e32 v38, v38
	v_cndmask_b32_e64 v39, 0, v236, s[36:37]
	s_mov_b32 s39, 63
	v_ldexp_f32 v108, v38, v39
	v_mul_f32_e32 v38, v1, v129
	v_cmp_gt_f32_e64 s[36:37], s52, v38
	v_mov_b32_e32 v109, v108
	v_mov_b32_e32 v110, v108
	v_cndmask_b32_e64 v38, 0, v234, s[36:37]
	v_fmac_f32_e32 v38, v1, v129
	v_exp_f32_e32 v38, v38
	v_cndmask_b32_e64 v39, 0, v236, s[36:37]
	v_mov_b32_e32 v111, v108
	v_ldexp_f32 v103, v38, v39
	v_mul_f32_e32 v38, v1, v130
	v_cmp_gt_f32_e64 s[36:37], s52, v38
	s_nop 1
	v_cndmask_b32_e64 v38, 0, v234, s[36:37]
	v_fmac_f32_e32 v38, v1, v130
	v_exp_f32_e32 v38, v38
	v_cndmask_b32_e64 v39, 0, v236, s[36:37]
	v_ldexp_f32 v198, v38, v39
	v_mul_f32_e32 v38, v1, v132
	v_cmp_gt_f32_e64 s[36:37], s52, v38
	s_nop 1
	v_cndmask_b32_e64 v38, 0, v234, s[36:37]
	v_fmac_f32_e32 v38, v1, v132
	v_exp_f32_e32 v38, v38
	v_cndmask_b32_e64 v39, 0, v236, s[36:37]
	v_ldexp_f32 v199, v38, v39
	v_mul_f32_e32 v38, v1, v133
	v_cmp_gt_f32_e64 s[36:37], s52, v38
	s_nop 1
	v_cndmask_b32_e64 v38, 0, v234, s[36:37]
	v_fmac_f32_e32 v38, v1, v133
	v_exp_f32_e32 v38, v38
	v_cndmask_b32_e64 v39, 0, v236, s[36:37]
	v_ldexp_f32 v200, v38, v39
	v_mul_f32_e32 v38, v1, v135
	v_cmp_gt_f32_e64 s[36:37], s52, v38
	s_nop 1
	v_cndmask_b32_e64 v38, 0, v234, s[36:37]
	v_fmac_f32_e32 v38, v1, v135
	v_exp_f32_e32 v38, v38
	v_cndmask_b32_e64 v39, 0, v236, s[36:37]
	v_ldexp_f32 v201, v38, v39
	v_mul_f32_e32 v38, v1, v136
	v_cmp_gt_f32_e64 s[36:37], s52, v38
	s_nop 1
	v_cndmask_b32_e64 v38, 0, v234, s[36:37]
	v_fmac_f32_e32 v38, v1, v136
	v_exp_f32_e32 v38, v38
	v_cndmask_b32_e64 v39, 0, v236, s[36:37]
	v_ldexp_f32 v202, v38, v39
	v_mul_f32_e32 v38, v1, v138
	v_cmp_gt_f32_e64 s[36:37], s52, v38
	s_nop 1
	v_cndmask_b32_e64 v38, 0, v234, s[36:37]
	v_fmac_f32_e32 v38, v1, v138
	v_exp_f32_e32 v38, v38
	v_cndmask_b32_e64 v39, 0, v236, s[36:37]
	v_ldexp_f32 v203, v38, v39
	v_mul_f32_e32 v38, v1, v139
	v_cmp_gt_f32_e64 s[36:37], s52, v38
	s_nop 1
	v_cndmask_b32_e64 v38, 0, v234, s[36:37]
	v_fmac_f32_e32 v38, v1, v139
	v_exp_f32_e32 v1, v38
	v_cndmask_b32_e64 v38, 0, v236, s[36:37]
	v_ldexp_f32 v204, v1, v38
	v_mov_b32_e32 v38, 0
	v_mov_b32_e32 v39, v38
	v_mov_b32_e32 v40, v38
	v_mov_b32_e32 v41, v38
	v_mov_b32_e32 v42, v38
	v_mov_b32_e32 v43, v38
	v_mov_b32_e32 v44, v38
	v_mov_b32_e32 v45, v38
	v_mov_b32_e32 v46, v38
	v_mov_b32_e32 v47, v38
	v_mov_b32_e32 v48, v38
	v_mov_b32_e32 v49, v38
	v_mov_b32_e32 v54, v38
	v_mov_b32_e32 v55, v38
	v_mov_b32_e32 v56, v38
	v_mov_b32_e32 v57, v38
	v_mov_b32_e32 v50, v38
	v_mov_b32_e32 v51, v38
	v_mov_b32_e32 v52, v38
	v_mov_b32_e32 v53, v38
	v_mov_b32_e32 v58, v38
	v_mov_b32_e32 v59, v38
	v_mov_b32_e32 v60, v38
	v_mov_b32_e32 v61, v38
	v_mov_b32_e32 v62, v38
	v_mov_b32_e32 v63, v38
	v_mov_b32_e32 v64, v38
	v_mov_b32_e32 v65, v38
	v_mov_b32_e32 v66, v38
	v_mov_b32_e32 v67, v38
	v_mov_b32_e32 v68, v38
	v_mov_b32_e32 v69, v38
	s_waitcnt vmcnt(0)
